# attention row-max chains (both head types): removed the s_nop 0 pads hipcc put behind inline-asm v_max3 and the redundant max(x,x) canonicalisations; otherwise v19
# speedup vs baseline: 1.0108x; 1.0108x over previous
; DI float max3f(float a, float b, float c) { float r; asm("v_max3_f32 %0, %1, %2, %3" : "=v"(r) : "v"(a), "v"(b), "v"(c)); return r; }
; template <int DK>
; DI void attn_pass(const AttnSrc& s, const int q0, const float sc, LAS unsigned char* lds, f32x16 (&O)[4]) {
;     ...
;         const int qa = qw0 + r, kbase = 64 * t + 4 * h;
; #pragma unroll
;         for (int j = 0; j < 16; ++j) { const int kv = kbase + (j & 3) + 8 * (j >> 2); if (kv > qa) p0[j] = -INFINITY; if (kv + 32 > qa) p1[j] = -INFINITY; }
;       }
;       asm volatile("s_nop 15\n\ts_nop 7" : "+v"(p0), "+v"(p1));
;       float mx;
;       { float ma = max3f(p0[0], p0[1], p1[0]), mb = max3f(p0[2], p0[3], p1[1]); ma = max3f(ma, p1[2], p1[3]);
; #pragma unroll
;         for (int j = 4; j < 16; j += 4) { ma = max3f(ma, p0[j], p0[j + 1]); mb = max3f(mb, p0[j + 2], p0[j + 3]); ma = max3f(ma, p1[j], p1[j + 1]); mb = max3f(mb, p1[j + 2], p1[j + 3]); }
;         mx = fmaxf(ma, mb); }
;       { auto rr = __builtin_amdgcn_permlane32_swap(__float_as_uint(mx), __float_as_uint(mx), false, false); mx = fmaxf(__uint_as_float(rr[0]), __uint_as_float(rr[1])); }
;       float rs = 0.f;
;       if (REL) {
;         const bool grow = (mx > 8.f) || (t == 0);
;         if (__builtin_amdgcn_ballot_w64(grow) != 0ull) {
;           const float dl = grow ? mx : 0.f;
;           const float alpha = __builtin_amdgcn_exp2f(-dl);
;           mrun += dl; lrun *= alpha;
; #pragma unroll
;           for (int j = 0; j < 16; ++j) { p0[j] -= dl; p1[j] -= dl; negm[j] = -mrun; }
;           asm volatile("" : "+v"(negm));
; #pragma unroll
;           for (int i = 0; i < 4; ++i)
; #pragma unroll
;             for (int j = 0; j < 16; ++j) O[i][j] *= alpha;
.Ln64_nomask:
	s_mov_b32 s18, 0x41000000
	v_max3_f32 v0, v112, v113, v96
	v_max3_f32 v230, v114, v115, v97
	s_cmp_eq_u32 s53, 63
	v_max3_f32 v0, v0, v98, v99
	v_max3_f32 v230, v230, v118, v119
	v_max3_f32 v0, v0, v116, v117
	v_max3_f32 v230, v230, v102, v103
	v_max3_f32 v0, v0, v100, v101
	v_max3_f32 v230, v230, v122, v123
	v_max3_f32 v0, v0, v120, v121
	v_max3_f32 v230, v230, v106, v107
	v_max3_f32 v0, v0, v104, v105
	v_max3_f32 v230, v230, v126, v127
	v_max3_f32 v0, v0, v124, v125
	v_max3_f32 v230, v230, v110, v111
	v_max3_f32 v0, v0, v108, v109
	v_max_f32_e32 v0, v0, v230
	v_mov_b32_e32 v230, v0
	s_nop 1
	v_permlane32_swap_b32_e32 v0, v230
	v_max_f32_e32 v0, v0, v230
	v_cmp_lt_f32_e32 vcc, s18, v0
	s_cselect_b64 s[18:19], -1, 0
	s_or_b64 vcc, s[18:19], vcc
	s_cbranch_vccz .Ln64_exp
	v_cndmask_b32_e32 v0, 0, v0, vcc
	v_add_f32_e32 v227, v227, v0
	v_pk_add_f32 v[112:113], v[112:113], v[0:1] op_sel_hi:[1,0] neg_lo:[0,1] neg_hi:[0,1]
	v_pk_add_f32 v[96:97], v[96:97], v[0:1] op_sel_hi:[1,0] neg_lo:[0,1] neg_hi:[0,1]
	v_pk_add_f32 v[114:115], v[114:115], v[0:1] op_sel_hi:[1,0] neg_lo:[0,1] neg_hi:[0,1]
	v_pk_add_f32 v[98:99], v[98:99], v[0:1] op_sel_hi:[1,0] neg_lo:[0,1] neg_hi:[0,1]
	v_pk_add_f32 v[116:117], v[116:117], v[0:1] op_sel_hi:[1,0] neg_lo:[0,1] neg_hi:[0,1]
	v_pk_add_f32 v[100:101], v[100:101], v[0:1] op_sel_hi:[1,0] neg_lo:[0,1] neg_hi:[0,1]
	v_pk_add_f32 v[118:119], v[118:119], v[0:1] op_sel_hi:[1,0] neg_lo:[0,1] neg_hi:[0,1]
	v_pk_add_f32 v[102:103], v[102:103], v[0:1] op_sel_hi:[1,0] neg_lo:[0,1] neg_hi:[0,1]
	v_pk_add_f32 v[120:121], v[120:121], v[0:1] op_sel_hi:[1,0] neg_lo:[0,1] neg_hi:[0,1]
	v_pk_add_f32 v[104:105], v[104:105], v[0:1] op_sel_hi:[1,0] neg_lo:[0,1] neg_hi:[0,1]
	v_pk_add_f32 v[122:123], v[122:123], v[0:1] op_sel_hi:[1,0] neg_lo:[0,1] neg_hi:[0,1]
	v_pk_add_f32 v[106:107], v[106:107], v[0:1] op_sel_hi:[1,0] neg_lo:[0,1] neg_hi:[0,1]
	v_pk_add_f32 v[124:125], v[124:125], v[0:1] op_sel_hi:[1,0] neg_lo:[0,1] neg_hi:[0,1]
	v_pk_add_f32 v[108:109], v[108:109], v[0:1] op_sel_hi:[1,0] neg_lo:[0,1] neg_hi:[0,1]
	v_pk_add_f32 v[126:127], v[126:127], v[0:1] op_sel_hi:[1,0] neg_lo:[0,1] neg_hi:[0,1]
	v_pk_add_f32 v[110:111], v[110:111], v[0:1] op_sel_hi:[1,0] neg_lo:[0,1] neg_hi:[0,1]
	v_exp_f32_e64 v0, -v0
	v_xor_b32_e32 v80, 0x80000000, v227
	v_mov_b32_e32 v81, v80
	v_mov_b32_e32 v82, v80
	v_mov_b32_e32 v83, v80
	v_mov_b32_e32 v84, v80
	v_mov_b32_e32 v85, v80
	v_mov_b32_e32 v86, v80
	v_mov_b32_e32 v87, v80
	v_mov_b32_e32 v88, v80
	v_mov_b32_e32 v89, v80
	v_mov_b32_e32 v90, v80
	v_mov_b32_e32 v91, v80
	v_mov_b32_e32 v92, v80
	v_mov_b32_e32 v93, v80
	v_mov_b32_e32 v94, v80
	v_mov_b32_e32 v95, v80
	v_pk_mul_f32 v[78:79], v[78:79], v[0:1] op_sel_hi:[1,0]
	v_pk_mul_f32 v[76:77], v[76:77], v[0:1] op_sel_hi:[1,0]
	v_pk_mul_f32 v[74:75], v[74:75], v[0:1] op_sel_hi:[1,0]
	v_pk_mul_f32 v[72:73], v[72:73], v[0:1] op_sel_hi:[1,0]
	v_pk_mul_f32 v[70:71], v[70:71], v[0:1] op_sel_hi:[1,0]
	v_pk_mul_f32 v[68:69], v[68:69], v[0:1] op_sel_hi:[1,0]
	v_pk_mul_f32 v[66:67], v[66:67], v[0:1] op_sel_hi:[1,0]
	v_pk_mul_f32 v[64:65], v[64:65], v[0:1] op_sel_hi:[1,0]
	v_pk_mul_f32 v[62:63], v[62:63], v[0:1] op_sel_hi:[1,0]
	v_pk_mul_f32 v[60:61], v[60:61], v[0:1] op_sel_hi:[1,0]
	v_pk_mul_f32 v[58:59], v[58:59], v[0:1] op_sel_hi:[1,0]
	v_pk_mul_f32 v[56:57], v[56:57], v[0:1] op_sel_hi:[1,0]
	v_pk_mul_f32 v[54:55], v[54:55], v[0:1] op_sel_hi:[1,0]
	v_pk_mul_f32 v[52:53], v[52:53], v[0:1] op_sel_hi:[1,0]
	v_pk_mul_f32 v[50:51], v[50:51], v[0:1] op_sel_hi:[1,0]
	v_pk_mul_f32 v[48:49], v[48:49], v[0:1] op_sel_hi:[1,0]
	v_pk_mul_f32 v[46:47], v[46:47], v[0:1] op_sel_hi:[1,0]
	v_pk_mul_f32 v[44:45], v[44:45], v[0:1] op_sel_hi:[1,0]
	v_pk_mul_f32 v[42:43], v[42:43], v[0:1] op_sel_hi:[1,0]
	v_pk_mul_f32 v[40:41], v[40:41], v[0:1] op_sel_hi:[1,0]
	v_pk_mul_f32 v[38:39], v[38:39], v[0:1] op_sel_hi:[1,0]
	v_pk_mul_f32 v[36:37], v[36:37], v[0:1] op_sel_hi:[1,0]
	v_pk_mul_f32 v[34:35], v[34:35], v[0:1] op_sel_hi:[1,0]
	v_pk_mul_f32 v[32:33], v[32:33], v[0:1] op_sel_hi:[1,0]
	v_pk_mul_f32 v[30:31], v[30:31], v[0:1] op_sel_hi:[1,0]
	v_pk_mul_f32 v[28:29], v[28:29], v[0:1] op_sel_hi:[1,0]
	v_pk_mul_f32 v[26:27], v[26:27], v[0:1] op_sel_hi:[1,0]
	v_pk_mul_f32 v[24:25], v[24:25], v[0:1] op_sel_hi:[1,0]
	v_pk_mul_f32 v[22:23], v[22:23], v[0:1] op_sel_hi:[1,0]
	v_pk_mul_f32 v[20:21], v[20:21], v[0:1] op_sel_hi:[1,0]
	v_pk_mul_f32 v[18:19], v[18:19], v[0:1] op_sel_hi:[1,0]
	v_pk_mul_f32 v[16:17], v[16:17], v[0:1] op_sel_hi:[1,0]
	v_mul_f32_e32 v14, v14, v0

; DI float max3f(float a, float b, float c) { float r; asm("v_max3_f32 %0, %1, %2, %3" : "=v"(r) : "v"(a), "v"(b), "v"(c)); return r; }
; template <int DK>
; DI void attn_pass(const AttnSrc& s, const int q0, const float sc, LAS unsigned char* lds, f32x16 (&O)[4]) {
;     ...
;       { float ma = max3f(p0[0], p0[1], p1[0]), mb = max3f(p0[2], p0[3], p1[1]); ma = max3f(ma, p1[2], p1[3]);
; #pragma unroll
;         for (int j = 4; j < 16; j += 4) { ma = max3f(ma, p0[j], p0[j + 1]); mb = max3f(mb, p0[j + 2], p0[j + 3]); ma = max3f(ma, p1[j], p1[j + 1]); mb = max3f(mb, p1[j + 2], p1[j + 3]); }
;         mx = fmaxf(ma, mb); }
;       { auto rr = __builtin_amdgcn_permlane32_swap(__float_as_uint(mx), __float_as_uint(mx), false, false); mx = fmaxf(__uint_as_float(rr[0]), __uint_as_float(rr[1])); }
;       float rs = 0.f;
;       if (REL) {
;         const bool grow = (mx > 8.f) || (t == 0);
;         if (__builtin_amdgcn_ballot_w64(grow) != 0ull) {
;           const float dl = grow ? mx : 0.f;
;           const float alpha = __builtin_amdgcn_exp2f(-dl);
;           mrun += dl; lrun *= alpha;
; #pragma unroll
;           for (int j = 0; j < 16; ++j) { p0[j] -= dl; p1[j] -= dl; negm[j] = -mrun; }
;           asm volatile("" : "+v"(negm));
; #pragma unroll
;           for (int i = 0; i < 4; ++i)
; #pragma unroll
;             for (int j = 0; j < 16; ++j) O[i][j] *= alpha;
;         }
; #pragma unroll
;         for (int j = 0; j < 16; ++j) { p0[j] = __builtin_amdgcn_exp2f(p0[j]); p1[j] = __builtin_amdgcn_exp2f(p1[j]); rs += p0[j] + p1[j]; }
;       } else {
;         const float cand = mx * sc;
;         const bool grow = cand > mrun + 8.f;
;         if (__builtin_amdgcn_ballot_w64(grow) != 0ull) {
;           const float mnew = grow ? cand : mrun;
;           const float alpha = __builtin_amdgcn_exp2f(mrun - mnew);
;           mrun = mnew; lrun *= alpha;
; #pragma unroll
;           for (int i = 0; i < 4; ++i)
; #pragma unroll
;             for (int j = 0; j < 16; ++j) O[i][j] *= alpha;
.Ln192_nomask:
	v_max3_f32 v0, v82, v83, v66
	v_max3_f32 v221, v84, v85, v67
	v_max3_f32 v0, v0, v68, v69
	v_max3_f32 v221, v221, v88, v89
	v_max3_f32 v0, v0, v86, v87
	v_max3_f32 v221, v221, v72, v73
	v_max3_f32 v0, v0, v70, v71
	v_max3_f32 v221, v221, v92, v93
	v_max3_f32 v0, v0, v90, v91
	v_max3_f32 v221, v221, v76, v77
	v_max3_f32 v0, v0, v74, v75
	v_max3_f32 v221, v221, v96, v97
	v_max3_f32 v0, v0, v94, v95
	v_max3_f32 v221, v221, v80, v81
	v_max3_f32 v0, v0, v78, v79
	v_max_f32_e32 v0, v0, v221
	v_mov_b32_e32 v221, v0
	s_nop 1
	v_permlane32_swap_b32_e32 v0, v221
	v_max_f32_e32 v0, v0, v221
	v_mul_f32_e32 v0, 0x3dd53b94, v0
	v_add_f32_e32 v221, 0x41000000, v219
	v_cmp_gt_f32_e32 vcc, v0, v221
	s_cbranch_vccz .Ln192_exp
	s_nop 0
	v_cndmask_b32_e32 v221, v219, v0, vcc
	v_sub_f32_e32 v0, v219, v221
	v_exp_f32_e32 v0, v0
	v_mov_b32_e32 v219, v221
	v_pk_mul_f32 v[64:65], v[64:65], v[0:1] op_sel_hi:[1,0]
	v_pk_mul_f32 v[62:63], v[62:63], v[0:1] op_sel_hi:[1,0]
	v_pk_mul_f32 v[60:61], v[60:61], v[0:1] op_sel_hi:[1,0]
	v_pk_mul_f32 v[58:59], v[58:59], v[0:1] op_sel_hi:[1,0]
	v_pk_mul_f32 v[56:57], v[56:57], v[0:1] op_sel_hi:[1,0]
	v_pk_mul_f32 v[54:55], v[54:55], v[0:1] op_sel_hi:[1,0]
	v_pk_mul_f32 v[52:53], v[52:53], v[0:1] op_sel_hi:[1,0]
	v_pk_mul_f32 v[50:51], v[50:51], v[0:1] op_sel_hi:[1,0]
	v_pk_mul_f32 v[48:49], v[48:49], v[0:1] op_sel_hi:[1,0]
	v_pk_mul_f32 v[46:47], v[46:47], v[0:1] op_sel_hi:[1,0]
	v_pk_mul_f32 v[44:45], v[44:45], v[0:1] op_sel_hi:[1,0]
	v_pk_mul_f32 v[42:43], v[42:43], v[0:1] op_sel_hi:[1,0]
	v_pk_mul_f32 v[40:41], v[40:41], v[0:1] op_sel_hi:[1,0]
	v_pk_mul_f32 v[38:39], v[38:39], v[0:1] op_sel_hi:[1,0]
	v_pk_mul_f32 v[36:37], v[36:37], v[0:1] op_sel_hi:[1,0]
	v_pk_mul_f32 v[34:35], v[34:35], v[0:1] op_sel_hi:[1,0]
	v_pk_mul_f32 v[32:33], v[32:33], v[0:1] op_sel_hi:[1,0]
	v_pk_mul_f32 v[30:31], v[30:31], v[0:1] op_sel_hi:[1,0]
	v_pk_mul_f32 v[28:29], v[28:29], v[0:1] op_sel_hi:[1,0]
	v_pk_mul_f32 v[26:27], v[26:27], v[0:1] op_sel_hi:[1,0]
	v_pk_mul_f32 v[24:25], v[24:25], v[0:1] op_sel_hi:[1,0]
	v_pk_mul_f32 v[22:23], v[22:23], v[0:1] op_sel_hi:[1,0]
	v_pk_mul_f32 v[20:21], v[20:21], v[0:1] op_sel_hi:[1,0]
	v_pk_mul_f32 v[18:19], v[18:19], v[0:1] op_sel_hi:[1,0]
	v_pk_mul_f32 v[16:17], v[16:17], v[0:1] op_sel_hi:[1,0]
	v_pk_mul_f32 v[14:15], v[14:15], v[0:1] op_sel_hi:[1,0]
	v_pk_mul_f32 v[12:13], v[12:13], v[0:1] op_sel_hi:[1,0]
	v_pk_mul_f32 v[10:11], v[10:11], v[0:1] op_sel_hi:[1,0]
	v_pk_mul_f32 v[8:9], v[8:9], v[0:1] op_sel_hi:[1,0]
	v_pk_mul_f32 v[6:7], v[6:7], v[0:1] op_sel_hi:[1,0]
	v_pk_mul_f32 v[4:5], v[4:5], v[0:1] op_sel_hi:[1,0]
	v_pk_mul_f32 v[2:3], v[2:3], v[0:1] op_sel_hi:[1,0]
	v_mul_f32_e32 v218, v218, v0
